# attn_combine work split 1:3 (scan blocks take a small share after their scan instead of none)
# baseline (speedup 1.0000x reference)
; __device__ __forceinline__ bf16* po_base(unsigned char* ws, int pat) { return (bf16*)(ws + (pat < 2 ? 436 * MiB + (size_t)pat * 32 * MiB : WS_Y)); }
; __device__ __forceinline__ void attn_combine(unsigned char* ws, const float* __restrict__ PM, bf16* CAT, int gtid, int gthreads, int iend = S * 128) {
;     for (int idx = gtid; idx < iend; idx += gthreads) {
;         const int t = idx >> 7, c = (idx & 127) * 8, hh = c >> 7;
;         float mm[3], ll[3];
; #pragma unroll
;         for (int p = 0; p < 3; ++p) { const f32x2_t ml = *(const f32x2_t*)(PM + (((size_t)p * S + t) * 8 + hh) * 2); mm[p] = ml[0]; ll[p] = ml[1]; }
;         const float ma = fmaxf(mm[0], fmaxf(mm[1], mm[2]));
;         float w[3], den = 0.f;
; #pragma unroll
;         for (int p = 0; p < 3; ++p) { w[p] = exp2f(mm[p] - ma) * ll[p]; den += w[p]; }
;         const float inv = 1.f / den;
;         float o[8] = {0.f, 0.f, 0.f, 0.f, 0.f, 0.f, 0.f, 0.f};
; #pragma unroll
;         for (int p = 0; p < 3; ++p) {
;             const u32x4 v = *(const u32x4*)(po_base(ws, p) + (size_t)t * 1024 + c); const float wp = w[p] * inv;
; __global__ void __launch_bounds__(512, 2) mega(Args a) {
;     ...
;             const long NIT = (long)S * 128, W = 192 * 5 + 64 * 3;
;             const long c0 = b <= NG ? 3L * b : 192L + 5L * (b - NG), c1 = (b + 1) <= NG ? 3L * (b + 1) : 192L + 5L * (b + 1 - NG);
;             const int i0 = (int)(NIT * c0 / W), i1 = (int)(NIT * c1 / W);
;             attn_combine(ws, PM, CAT, i0 + tid, 512, i1);
.LBB0_790:
	s_lshl_b64 s[4:5], s[0:1], 21
	s_lshr_b64 s[0:1], s[0:1], 11
	s_mul_hi_u32 s6, s4, 0xe38e38e
	s_mul_i32 s7, s4, 0xe38e38e
	s_mul_i32 s8, s0, 0x38e38e39
	s_mul_hi_u32 s4, s4, 0x38e38e39
	s_mul_hi_u32 s1, s0, 0x38e38e39
	s_add_u32 s4, s8, s4
	s_addc_u32 s1, s1, 0
	s_add_u32 s4, s7, s4
	s_addc_u32 s4, s6, 0
	s_add_u32 s1, s1, s4
	s_addc_u32 s4, 0, 0
	s_mul_hi_u32 s6, s0, 0xe38e38e
	s_mul_i32 s0, s0, 0xe38e38e
	s_add_u32 s0, s0, s1
	s_addc_u32 s1, s6, s4
	s_ashr_i32 s4, s5, 31
	s_mul_i32 s5, s4, 0xe38e38e
	s_mul_hi_u32 s6, s4, 0x38e38e39
	s_add_i32 s5, s6, s5
	s_mul_i32 s4, s4, 0x38e38e39
	s_add_i32 s5, s5, s4
	s_add_u32 s0, s0, s4
	s_addc_u32 s1, s1, s5
	s_lshr_b32 s4, s1, 31
	s_lshr_b64 s[0:1], s[0:1], 6
	s_add_i32 s4, s0, s4
	s_lshl_b64 s[0:1], s[2:3], 21
	s_lshr_b64 s[2:3], s[2:3], 11
	s_mul_hi_u32 s5, s0, 0xe38e38e
	s_mul_i32 s6, s0, 0xe38e38e
	s_mul_i32 s7, s2, 0x38e38e39
	s_mul_hi_u32 s0, s0, 0x38e38e39
	s_mul_hi_u32 s3, s2, 0x38e38e39
	s_add_u32 s0, s7, s0
	s_addc_u32 s3, s3, 0
	s_add_u32 s0, s6, s0
	s_addc_u32 s0, s5, 0
	s_add_u32 s0, s3, s0
	s_addc_u32 s3, 0, 0
	s_mul_hi_u32 s5, s2, 0xe38e38e
	s_mul_i32 s2, s2, 0xe38e38e
	s_add_u32 s0, s2, s0
	s_addc_u32 s2, s5, s3
	s_ashr_i32 s1, s1, 31
	s_mul_i32 s3, s1, 0xe38e38e
	s_mul_hi_u32 s5, s1, 0x38e38e39
	s_add_i32 s3, s5, s3
	s_mul_i32 s1, s1, 0x38e38e39
	s_add_i32 s3, s3, s1
	s_add_u32 s0, s0, s1
	s_addc_u32 s1, s2, s3
	s_lshr_b32 s2, s1, 31
	s_lshr_b64 s[0:1], s[0:1], 6
	s_add_i32 s18, s0, s2
	s_mov_b64 s[2:3], exec
	s_cmp_lt_i32 s66, 64
	s_cbranch_scc1 .Lcmb_small
	s_mul_i32 s4, s66, 3
	s_sub_i32 s4, s4, 128
	s_add_i32 s18, s4, 3
	s_branch .Lcmb_split
.Lcmb_small:
	s_mov_b32 s4, s66
	s_add_i32 s18, s66, 1
.Lcmb_split:
	s_lshl_b32 s4, s4, 14
	s_lshl_b32 s18, s18, 14
	s_mul_hi_u32 s4, s4, 0xcccccccd
	s_lshr_b32 s4, s4, 2
	s_mul_hi_u32 s18, s18, 0xcccccccd
	s_lshr_b32 s18, s18, 2
	v_add_u32_e32 v2, s4, v186
	v_readlane_b32 s26, v245, 38
	v_readlane_b32 s27, v245, 39
	s_add_u32 s6, s88, 0x600000
	s_addc_u32 s7, s89, 0
	s_add_u32 s8, s88, 0x700000
	s_addc_u32 s9, s89, 0
	s_add_u32 s16, s88, 0x1b400000
	s_addc_u32 s17, s89, 0
	s_add_u32 s20, s88, 0x1d400000
	s_addc_u32 s21, s89, 0
	v_readlane_b32 s22, v245, 15
	v_readlane_b32 s23, v245, 16
	s_sub_i32 s0, s18, s4
	s_add_i32 s0, s0, 2047
	s_lshr_b32 s0, s0, 11
	s_add_i32 s1, s18, -1
	s_mov_b32 s19, 0xc2fc0000
	v_mov_b32_e32 v1, 0
	v_mov_b32_e32 v4, 0x42800000
	v_not_b32_e32 v5, 63
	v_min_i32_e32 v60, s1, v2
	v_ashrrev_i32_e32 v59, 7, v60
	v_lshrrev_b32_e32 v61, 1, v60
	v_and_b32_e32 v61, 56, v61
	v_lshl_or_b32 v61, v59, 6, v61
	global_load_dwordx2 v[40:41], v61, s[26:27]
	global_load_dwordx2 v[42:43], v61, s[6:7]
	global_load_dwordx2 v[44:45], v61, s[8:9]
	v_and_b32_e32 v58, 0x7f, v60
	v_lshlrev_b32_e32 v60, 4, v60
	v_lshlrev_b32_e32 v58, 4, v58
	global_load_dwordx4 v[46:49], v60, s[16:17]
	v_lshl_or_b32 v58, v59, 12, v58
	global_load_dwordx4 v[50:53], v60, s[20:21]
	global_load_dwordx4 v[54:57], v60, s[22:23]
	v_add_u32_e32 v84, 512, v2
	v_min_i32_e32 v84, s1, v84
	v_ashrrev_i32_e32 v83, 7, v84
	v_lshrrev_b32_e32 v85, 1, v84
	v_and_b32_e32 v85, 56, v85
	v_lshl_or_b32 v85, v83, 6, v85
	global_load_dwordx2 v[64:65], v85, s[26:27]
	global_load_dwordx2 v[66:67], v85, s[6:7]
	global_load_dwordx2 v[68:69], v85, s[8:9]
	v_and_b32_e32 v82, 0x7f, v84
	v_lshlrev_b32_e32 v84, 4, v84
	v_lshlrev_b32_e32 v82, 4, v82
	global_load_dwordx4 v[70:73], v84, s[16:17]
	v_lshl_or_b32 v82, v83, 12, v82
	global_load_dwordx4 v[74:77], v84, s[20:21]
	global_load_dwordx4 v[78:81], v84, s[22:23]
	v_add_u32_e32 v108, 1024, v2
	v_min_i32_e32 v108, s1, v108
	v_ashrrev_i32_e32 v107, 7, v108
	v_lshrrev_b32_e32 v109, 1, v108
	v_and_b32_e32 v109, 56, v109
	v_lshl_or_b32 v109, v107, 6, v109
	global_load_dwordx2 v[88:89], v109, s[26:27]
	global_load_dwordx2 v[90:91], v109, s[6:7]
	global_load_dwordx2 v[92:93], v109, s[8:9]
	v_and_b32_e32 v106, 0x7f, v108
	v_lshlrev_b32_e32 v108, 4, v108
	v_lshlrev_b32_e32 v106, 4, v106
	global_load_dwordx4 v[94:97], v108, s[16:17]
	v_lshl_or_b32 v106, v107, 12, v106
	global_load_dwordx4 v[98:101], v108, s[20:21]
	global_load_dwordx4 v[102:105], v108, s[22:23]
	v_add_u32_e32 v132, 1536, v2
	v_min_i32_e32 v132, s1, v132
	v_ashrrev_i32_e32 v131, 7, v132
	v_lshrrev_b32_e32 v133, 1, v132
	v_and_b32_e32 v133, 56, v133
	v_lshl_or_b32 v133, v131, 6, v133
	global_load_dwordx2 v[112:113], v133, s[26:27]
	global_load_dwordx2 v[114:115], v133, s[6:7]
	global_load_dwordx2 v[116:117], v133, s[8:9]
	v_and_b32_e32 v130, 0x7f, v132
	v_lshlrev_b32_e32 v132, 4, v132
	v_lshlrev_b32_e32 v130, 4, v130
	global_load_dwordx4 v[118:121], v132, s[16:17]
	v_lshl_or_b32 v130, v131, 12, v130
	global_load_dwordx4 v[122:125], v132, s[20:21]
	global_load_dwordx4 v[126:129], v132, s[22:23]
	v_add_u32_e32 v2, 2048, v2
